# indexer group loop: 8 key-fragment LDS reads issued up front, counted waits (on top of scan + prep edits)
# speedup vs baseline: 1.0310x; 1.0093x over previous
; DI f32x4 mfma16(bf16x8 a, bf16x8 b, f32x4 c) { return __builtin_amdgcn_mfma_f32_16x16x32_bf16(a, b, c, 0, 0, 0); }
; DI float relu_(float x) { return __builtin_amdgcn_fmed3f(x, 0.f, __builtin_inff()); }
; DI void dsa_task(const Params& p, int l, int isP, int b, int tq, char* smem, const bool dry) {
;     ...
;         for (int tg = 0; tg < ngrp; tg++) {
;           unsigned keys[4];
; #pragma unroll
;           for (int tt = 0; tt < 4; tt++) {
;             const bf16_t* br = kst + ((tg * 4 + tt) * 16 + cl) * 72 + g4 * 8;
;             const bf16x8 b0 = *(const bf16x8*)br;
;             const bf16x8 b1 = *(const bf16x8*)(br + 32);
;             f32x4 a = (f32x4){0.f, 0.f, 0.f, 0.f};
;             a = mfma16(aq0, b0, a);
;             a = mfma16(aq1, b1, a);
;             const float score = wq.x * relu_(a[0]) + wq.y * relu_(a[1]) + wq.z * relu_(a[2]) + wq.w * relu_(a[3]);
;             keys[tt] = mono_key(score);
;           }
.LBB0_1311:
	ds_read_b128 v[224:227], v123
	ds_read_b128 v[228:231], v123 offset:64
	ds_read_b128 v[232:235], v123 offset:2304
	ds_read_b128 v[236:239], v123 offset:2368
	ds_read_b128 v[240:243], v123 offset:4608
	ds_read_b128 v[244:247], v123 offset:4672
	ds_read_b128 v[248:251], v123 offset:6912
	ds_read_b128 v[124:127], v123 offset:6976
	s_cmp_lt_i32 s76, 5
	s_waitcnt lgkmcnt(7)
	v_mfma_f32_16x16x32_bf16 v[60:63], v[4:7], v[224:227], 0
	s_waitcnt lgkmcnt(5)
	v_mfma_f32_16x16x32_bf16 v[56:59], v[4:7], v[232:235], 0
	s_waitcnt lgkmcnt(3)
	v_mfma_f32_16x16x32_bf16 v[52:55], v[4:7], v[240:243], 0
	s_waitcnt lgkmcnt(1)
	v_mfma_f32_16x16x32_bf16 v[48:51], v[4:7], v[248:251], 0
	v_mfma_f32_16x16x32_bf16 v[60:63], v[8:11], v[228:231], v[60:63]
	v_mfma_f32_16x16x32_bf16 v[56:59], v[8:11], v[236:239], v[56:59]
	v_mfma_f32_16x16x32_bf16 v[52:55], v[8:11], v[244:247], v[52:55]
	s_waitcnt lgkmcnt(0)
	v_mfma_f32_16x16x32_bf16 v[48:51], v[8:11], v[124:127], v[48:51]
	s_cbranch_scc1 .LBB0_1313
	s_cmp_lg_u32 s76, 5
	s_mov_b64 s[38:39], -1
	s_cselect_b64 s[40:41], -1, 0
	s_cbranch_execz .LBB0_1314
	s_branch .LBB0_1315
